# grid-barrier acquire invalidate issued before the release poll (L1 drop overlaps the wait) + static leading-half priority + up-GEMM row-scale prefetch
# speedup vs baseline: 1.0118x; 1.0050x over previous
; __device__ __forceinline__ unsigned xb_ld(unsigned* p)              { return __hip_atomic_load(p, __ATOMIC_RELAXED, __HIP_MEMORY_SCOPE_AGENT); }
; __device__ __forceinline__ unsigned xb_add(unsigned* p, unsigned v) { return __hip_atomic_fetch_add(p, v, __ATOMIC_RELAXED, __HIP_MEMORY_SCOPE_AGENT); }
; #define XB_SPIN(cond, bar) do { unsigned _sp = 0; while (cond) { __builtin_amdgcn_s_sleep(1); \
;     if ((++_sp & 255u) == 0u) { if (xb_ld(&(bar)[XB_TMO])) break; if (_sp > XB_SPIN_CAP) { atomicAdd(&(bar)[XB_TMO], 1u); break; } } } } while (0)
; __device__ __forceinline__ void xcd_barrier(const XcdBarrier& b, int tid_in) {
;     ...
;         const unsigned gen = old / nloc;
;         if (old + 1u == (gen + 1u) * nloc) {
;             __builtin_amdgcn_fence(__ATOMIC_RELEASE, "agent");
;             asm volatile("s_waitcnt vmcnt(0)" ::: "memory");
;             const unsigned og = xb_add(&bar[XB_TOP], 1u);
;             const unsigned tg = og / nx;
;             if (og + 1u == (tg + 1u) * nx) xb_add(&bar[XB_TOPGEN], 1u);
;             else XB_SPIN(xb_ld(&bar[XB_TOPGEN]) == tg, bar);
;             __builtin_amdgcn_fence(__ATOMIC_ACQUIRE, "agent");
;             xb_add(&bar[XB_XGEN(b.x)], 1u);
;             asm volatile("s_waitcnt vmcnt(0)" ::: "memory");
;         } else {
;             XB_SPIN(xb_ld(&bar[XB_XGEN(b.x)]) == gen, bar);
;             __builtin_amdgcn_fence(__ATOMIC_ACQUIRE, "agent");
.LBB0_225:
	s_or_b64 exec, exec, s[12:13]
	v_cvt_f32_u32_e32 v5, v3
	s_waitcnt vmcnt(0)
	v_readfirstlane_b32 s2, v4
	v_sub_u32_e32 v4, 0, v3
	v_rcp_iflag_f32_e32 v5, v5
	v_add_u32_e32 v6, s2, v2
	v_mul_f32_e32 v5, 0x4f7ffffe, v5
	v_cvt_u32_f32_e32 v5, v5
	v_mul_lo_u32 v2, v4, v5
	v_mul_hi_u32 v2, v5, v2
	v_add_u32_e32 v2, v5, v2
	v_mul_hi_u32 v2, v6, v2
	v_mul_lo_u32 v4, v2, v3
	v_sub_u32_e32 v4, v6, v4
	v_add_u32_e32 v5, 1, v2
	v_cmp_ge_u32_e32 vcc, v4, v3
	s_nop 1
	v_cndmask_b32_e32 v2, v2, v5, vcc
	v_sub_u32_e32 v5, v4, v3
	v_cndmask_b32_e32 v4, v4, v5, vcc
	v_add_u32_e32 v5, 1, v2
	v_cmp_ge_u32_e32 vcc, v4, v3
	v_add_u32_e32 v4, 1, v6
	s_nop 0
	v_cndmask_b32_e32 v2, v2, v5, vcc
	v_mul_lo_u32 v5, v3, v2
	v_add_u32_e32 v3, v5, v3
	v_cmp_ne_u32_e32 vcc, v4, v3
	s_and_saveexec_b64 s[10:11], vcc
	s_xor_b64 s[10:11], exec, s[10:11]
	s_cbranch_execz .LBB0_239
	s_waitcnt lgkmcnt(0)
	buffer_inv sc1
	global_load_dword v0, v211, s[8:9] offset:1024 sc1
	s_add_u32 s16, s8, 0x2400
	s_addc_u32 s17, s9, 0
	s_waitcnt vmcnt(0)
	v_cmp_eq_u32_e32 vcc, v0, v2
	s_and_saveexec_b64 s[12:13], vcc
	s_cbranch_execz .LBB0_238
	s_add_u32 s14, s6, 0x10200
	s_addc_u32 s15, s7, 0
	s_mov_b32 s2, 1
	s_mov_b64 s[18:19], 0
	s_branch .LBB0_229

; __device__ __forceinline__ unsigned xb_ld(unsigned* p)              { return __hip_atomic_load(p, __ATOMIC_RELAXED, __HIP_MEMORY_SCOPE_AGENT); }
; #define XB_SPIN(cond, bar) do { unsigned _sp = 0; while (cond) { __builtin_amdgcn_s_sleep(1); \
;     if ((++_sp & 255u) == 0u) { if (xb_ld(&(bar)[XB_TMO])) break; if (_sp > XB_SPIN_CAP) { atomicAdd(&(bar)[XB_TMO], 1u); break; } } } } while (0)
; __device__ __forceinline__ void xcd_barrier(const XcdBarrier& b, int tid_in) {
;     ...
;             XB_SPIN(xb_ld(&bar[XB_XGEN(b.x)]) == gen, bar);
;             __builtin_amdgcn_fence(__ATOMIC_ACQUIRE, "agent");
;             asm volatile("s_waitcnt vmcnt(0)" ::: "memory");
.LBB0_238:
	s_or_b64 exec, exec, s[12:13]
	s_waitcnt vmcnt(0)
	s_waitcnt vmcnt(0)

; __device__ __forceinline__ unsigned xb_ld(unsigned* p)              { return __hip_atomic_load(p, __ATOMIC_RELAXED, __HIP_MEMORY_SCOPE_AGENT); }
; __device__ __forceinline__ unsigned xb_add(unsigned* p, unsigned v) { return __hip_atomic_fetch_add(p, v, __ATOMIC_RELAXED, __HIP_MEMORY_SCOPE_AGENT); }
; #define XB_SPIN(cond, bar) do { unsigned _sp = 0; while (cond) { __builtin_amdgcn_s_sleep(1); \
;     if ((++_sp & 255u) == 0u) { if (xb_ld(&(bar)[XB_TMO])) break; if (_sp > XB_SPIN_CAP) { atomicAdd(&(bar)[XB_TMO], 1u); break; } } } } while (0)
; __device__ __forceinline__ void xcd_barrier(const XcdBarrier& b, int tid_in) {
;     ...
;             __builtin_amdgcn_fence(__ATOMIC_RELEASE, "agent");
;             asm volatile("s_waitcnt vmcnt(0)" ::: "memory");
;             const unsigned og = xb_add(&bar[XB_TOP], 1u);
;             const unsigned tg = og / nx;
;             if (og + 1u == (tg + 1u) * nx) xb_add(&bar[XB_TOPGEN], 1u);
;             else XB_SPIN(xb_ld(&bar[XB_TOPGEN]) == tg, bar);
.LBB0_242:
	s_or_b64 exec, exec, s[12:13]
	v_cvt_f32_u32_e32 v4, v0
	s_waitcnt vmcnt(0)
	buffer_inv sc1
	v_readfirstlane_b32 s2, v3
	s_add_u32 s10, s6, 0x13500
	s_addc_u32 s11, s7, 0
	v_rcp_iflag_f32_e32 v4, v4
	v_add_u32_e32 v2, s2, v2
	v_add_u32_e32 v5, 1, v2
	s_mov_b64 s[14:15], -1
	v_mul_f32_e32 v3, 0x4f7ffffe, v4
	v_cvt_u32_f32_e32 v3, v3
	v_sub_u32_e32 v4, 0, v0
	v_mul_lo_u32 v4, v4, v3
	v_mul_hi_u32 v4, v3, v4
	v_add_u32_e32 v3, v3, v4
	v_mul_hi_u32 v3, v2, v3
	v_mul_lo_u32 v4, v3, v0
	v_sub_u32_e32 v2, v2, v4
	v_add_u32_e32 v6, 1, v3
	v_cmp_ge_u32_e32 vcc, v2, v0
	v_sub_u32_e32 v4, v2, v0
	s_nop 0
	v_cndmask_b32_e32 v3, v3, v6, vcc
	v_cndmask_b32_e32 v2, v2, v4, vcc
	v_add_u32_e32 v4, 1, v3
	v_cmp_ge_u32_e32 vcc, v2, v0
	s_nop 1
	v_cndmask_b32_e32 v4, v3, v4, vcc
	v_mul_lo_u32 v2, v0, v4
	v_add_u32_e32 v0, v2, v0
	v_cmp_ne_u32_e32 vcc, v5, v0
	v_mov_b64_e32 v[2:3], s[10:11]
	s_and_saveexec_b64 s[12:13], vcc
	s_cbranch_execz .LBB0_254
	global_load_dword v0, v1, s[10:11] sc1
	s_mov_b64 s[18:19], 0
	s_waitcnt vmcnt(0)
	v_cmp_eq_u32_e32 vcc, v0, v4
	s_and_saveexec_b64 s[16:17], vcc
	s_cbranch_execz .LBB0_253
	s_add_u32 s14, s6, 0x10200
	s_addc_u32 s15, s7, 0
	s_mov_b32 s2, 1
	s_mov_b64 s[6:7], 0
	s_branch .LBB0_246

; __device__ __forceinline__ unsigned xb_add(unsigned* p, unsigned v) { return __hip_atomic_fetch_add(p, v, __ATOMIC_RELAXED, __HIP_MEMORY_SCOPE_AGENT); }
; __device__ __forceinline__ void xcd_barrier(const XcdBarrier& b, int tid_in) {
;     ...
;             __builtin_amdgcn_fence(__ATOMIC_ACQUIRE, "agent");
;             xb_add(&bar[XB_XGEN(b.x)], 1u);
;             asm volatile("s_waitcnt vmcnt(0)" ::: "memory");
.LBB0_256:
	s_or_b64 exec, exec, s[6:7]
	s_mov_b64 s[6:7], exec
	v_mbcnt_lo_u32_b32 v0, s6, 0
	v_mbcnt_hi_u32_b32 v0, s7, v0
	v_cmp_eq_u32_e32 vcc, 0, v0
	s_waitcnt vmcnt(0)
	s_and_saveexec_b64 s[10:11], vcc
	s_cbranch_execz .LBB0_258
	s_bcnt1_i32_b64 s2, s[6:7]
	v_mov_b32_e32 v0, s2
	global_atomic_add v211, v0, s[8:9] offset:1024

; __device__ __forceinline__ unsigned xb_ld(unsigned* p)              { return __hip_atomic_load(p, __ATOMIC_RELAXED, __HIP_MEMORY_SCOPE_AGENT); }
; __device__ __forceinline__ unsigned xb_add(unsigned* p, unsigned v) { return __hip_atomic_fetch_add(p, v, __ATOMIC_RELAXED, __HIP_MEMORY_SCOPE_AGENT); }
; #define XB_SPIN(cond, bar) do { unsigned _sp = 0; while (cond) { __builtin_amdgcn_s_sleep(1); \
;     if ((++_sp & 255u) == 0u) { if (xb_ld(&(bar)[XB_TMO])) break; if (_sp > XB_SPIN_CAP) { atomicAdd(&(bar)[XB_TMO], 1u); break; } } } } while (0)
; __device__ __forceinline__ void xcd_barrier(const XcdBarrier& b, int tid_in) {
;     ...
;         const unsigned gen = old / nloc;
;         if (old + 1u == (gen + 1u) * nloc) {
;             __builtin_amdgcn_fence(__ATOMIC_RELEASE, "agent");
;             asm volatile("s_waitcnt vmcnt(0)" ::: "memory");
;             const unsigned og = xb_add(&bar[XB_TOP], 1u);
;             const unsigned tg = og / nx;
;             if (og + 1u == (tg + 1u) * nx) xb_add(&bar[XB_TOPGEN], 1u);
;             else XB_SPIN(xb_ld(&bar[XB_TOPGEN]) == tg, bar);
;             __builtin_amdgcn_fence(__ATOMIC_ACQUIRE, "agent");
;             xb_add(&bar[XB_XGEN(b.x)], 1u);
;             asm volatile("s_waitcnt vmcnt(0)" ::: "memory");
;         } else {
;             XB_SPIN(xb_ld(&bar[XB_XGEN(b.x)]) == gen, bar);
;             __builtin_amdgcn_fence(__ATOMIC_ACQUIRE, "agent");
.LBB0_1024:
	s_or_b64 exec, exec, s[12:13]
	v_cvt_f32_u32_e32 v5, v3
	s_waitcnt vmcnt(0)
	v_readfirstlane_b32 s10, v4
	v_sub_u32_e32 v4, 0, v3
	v_rcp_iflag_f32_e32 v5, v5
	v_add_u32_e32 v6, s10, v2
	v_mul_f32_e32 v5, 0x4f7ffffe, v5
	v_cvt_u32_f32_e32 v5, v5
	v_mul_lo_u32 v2, v4, v5
	v_mul_hi_u32 v2, v5, v2
	v_add_u32_e32 v2, v5, v2
	v_mul_hi_u32 v2, v6, v2
	v_mul_lo_u32 v4, v2, v3
	v_sub_u32_e32 v4, v6, v4
	v_add_u32_e32 v5, 1, v2
	v_cmp_ge_u32_e32 vcc, v4, v3
	s_nop 1
	v_cndmask_b32_e32 v2, v2, v5, vcc
	v_sub_u32_e32 v5, v4, v3
	v_cndmask_b32_e32 v4, v4, v5, vcc
	v_add_u32_e32 v5, 1, v2
	v_cmp_ge_u32_e32 vcc, v4, v3
	v_add_u32_e32 v4, 1, v6
	s_nop 0
	v_cndmask_b32_e32 v2, v2, v5, vcc
	v_mul_lo_u32 v5, v3, v2
	v_add_u32_e32 v3, v5, v3
	v_cmp_ne_u32_e32 vcc, v4, v3
	s_and_saveexec_b64 s[10:11], vcc
	s_xor_b64 s[10:11], exec, s[10:11]
	s_cbranch_execz .LBB0_1038
	s_waitcnt lgkmcnt(0)
	buffer_inv sc1
	global_load_dword v0, v211, s[8:9] offset:1024 sc1
	s_add_u32 s16, s8, 0x2400
	s_addc_u32 s17, s9, 0
	s_waitcnt vmcnt(0)
	v_cmp_eq_u32_e32 vcc, v0, v2
	s_and_saveexec_b64 s[12:13], vcc
	s_cbranch_execz .LBB0_1037
	s_add_u32 s14, s6, 0x10200
	s_addc_u32 s15, s7, 0
	s_mov_b32 s28, 1
	s_mov_b64 s[18:19], 0
	s_branch .LBB0_1028

; __device__ __forceinline__ unsigned xb_ld(unsigned* p)              { return __hip_atomic_load(p, __ATOMIC_RELAXED, __HIP_MEMORY_SCOPE_AGENT); }
; __device__ __forceinline__ unsigned xb_add(unsigned* p, unsigned v) { return __hip_atomic_fetch_add(p, v, __ATOMIC_RELAXED, __HIP_MEMORY_SCOPE_AGENT); }
; #define XB_SPIN(cond, bar) do { unsigned _sp = 0; while (cond) { __builtin_amdgcn_s_sleep(1); \
;     if ((++_sp & 255u) == 0u) { if (xb_ld(&(bar)[XB_TMO])) break; if (_sp > XB_SPIN_CAP) { atomicAdd(&(bar)[XB_TMO], 1u); break; } } } } while (0)
; __device__ __forceinline__ void xcd_barrier(const XcdBarrier& b, int tid_in) {
;     ...
;             __builtin_amdgcn_fence(__ATOMIC_RELEASE, "agent");
;             asm volatile("s_waitcnt vmcnt(0)" ::: "memory");
;             const unsigned og = xb_add(&bar[XB_TOP], 1u);
;             const unsigned tg = og / nx;
;             if (og + 1u == (tg + 1u) * nx) xb_add(&bar[XB_TOPGEN], 1u);
;             else XB_SPIN(xb_ld(&bar[XB_TOPGEN]) == tg, bar);
.LBB0_1041:
	s_or_b64 exec, exec, s[12:13]
	v_cvt_f32_u32_e32 v4, v0
	s_waitcnt vmcnt(0)
	buffer_inv sc1
	v_readfirstlane_b32 s10, v3
	s_mov_b64 s[14:15], -1
	v_rcp_iflag_f32_e32 v4, v4
	v_add_u32_e32 v2, s10, v2
	v_add_u32_e32 v5, 1, v2
	s_add_u32 s10, s6, 0x13500
	v_mul_f32_e32 v3, 0x4f7ffffe, v4
	v_cvt_u32_f32_e32 v3, v3
	v_sub_u32_e32 v4, 0, v0
	s_addc_u32 s11, s7, 0
	v_mul_lo_u32 v4, v4, v3
	v_mul_hi_u32 v4, v3, v4
	v_add_u32_e32 v3, v3, v4
	v_mul_hi_u32 v3, v2, v3
	v_mul_lo_u32 v4, v3, v0
	v_sub_u32_e32 v2, v2, v4
	v_add_u32_e32 v6, 1, v3
	v_cmp_ge_u32_e32 vcc, v2, v0
	v_sub_u32_e32 v4, v2, v0
	s_nop 0
	v_cndmask_b32_e32 v3, v3, v6, vcc
	v_cndmask_b32_e32 v2, v2, v4, vcc
	v_add_u32_e32 v4, 1, v3
	v_cmp_ge_u32_e32 vcc, v2, v0
	s_nop 1
	v_cndmask_b32_e32 v4, v3, v4, vcc
	v_mul_lo_u32 v2, v0, v4
	v_add_u32_e32 v0, v2, v0
	v_cmp_ne_u32_e32 vcc, v5, v0
	v_mov_b64_e32 v[2:3], s[10:11]
	s_and_saveexec_b64 s[12:13], vcc
	s_cbranch_execz .LBB0_1053
	global_load_dword v0, v1, s[10:11] sc1
	s_mov_b64 s[18:19], 0
	s_waitcnt vmcnt(0)
	v_cmp_eq_u32_e32 vcc, v0, v4
	s_and_saveexec_b64 s[16:17], vcc
	s_cbranch_execz .LBB0_1052
	s_add_u32 s14, s6, 0x10200
	s_addc_u32 s15, s7, 0
	s_mov_b32 s26, 1
	s_mov_b64 s[6:7], 0
	s_branch .LBB0_1045

; __device__ __forceinline__ unsigned xb_add(unsigned* p, unsigned v) { return __hip_atomic_fetch_add(p, v, __ATOMIC_RELAXED, __HIP_MEMORY_SCOPE_AGENT); }
; __device__ __forceinline__ void xcd_barrier(const XcdBarrier& b, int tid_in) {
;     ...
;             __builtin_amdgcn_fence(__ATOMIC_ACQUIRE, "agent");
;             xb_add(&bar[XB_XGEN(b.x)], 1u);
;             asm volatile("s_waitcnt vmcnt(0)" ::: "memory");
.LBB0_1055:
	s_or_b64 exec, exec, s[6:7]
	s_mov_b64 s[6:7], exec
	v_mbcnt_lo_u32_b32 v0, s6, 0
	v_mbcnt_hi_u32_b32 v0, s7, v0
	v_cmp_eq_u32_e32 vcc, 0, v0
	s_waitcnt vmcnt(0)
	s_and_saveexec_b64 s[10:11], vcc
	s_cbranch_execz .LBB0_164
	s_bcnt1_i32_b64 s6, s[6:7]
	v_mov_b32_e32 v0, s6
	global_atomic_add v211, v0, s[8:9] offset:1024
	s_branch .LBB0_164
